# v6 + norm_rows_fp8 row loop keeps two rows of x in flight (two alternating prefetch buffers refilled right after being consumed)
# baseline (speedup 1.0000x reference)
.LBB0_207:
	s_or_b64 exec, exec, s[0:1]
	v_readlane_b32 s0, v247, 2
	v_readlane_b32 s1, v247, 3
	v_readlane_b32 s0, v247, 0
	v_readlane_b32 s6, v247, 8
	s_lshl_b32 s18, s0, 2
	s_lshl_b32 s30, s6, 2
	v_add_u32_e32 v132, s18, v129
	s_mov_b32 s19, 0x8000
	v_add_u32_e32 v138, s30, v132
	v_readlane_b32 s1, v247, 1
	v_cmp_gt_i32_e64 s[34:35], s19, v132
	v_ashrrev_i32_e32 v133, 31, v132
	v_mbcnt_lo_u32_b32 v192, -1, 0
	v_ashrrev_i32_e32 v139, 31, v138
	s_waitcnt lgkmcnt(0)
	s_barrier
	v_readlane_b32 s2, v247, 4
	v_readlane_b32 s3, v247, 5
	v_readlane_b32 s4, v247, 6
	v_readlane_b32 s5, v247, 7
	v_readlane_b32 s7, v247, 9
	s_and_saveexec_b64 s[0:1], s[34:35]
	s_cbranch_execz .LBB0_214
	v_readlane_b32 s36, v247, 13
	v_readlane_b32 s37, v247, 14
	v_lshlrev_b64 v[0:1], 12, v[132:133]
	s_mov_b64 s[12:13], s[36:37]
	v_lshl_add_u64 v[0:1], s[12:13], 0, v[0:1]
	v_lshlrev_b32_e32 v40, 4, v128
	v_mov_b32_e32 v41, 0
	v_lshl_add_u64 v[0:1], v[0:1], 0, v[40:41]
	v_mov_b64_e32 v[126:127], v[0:1]
	v_mbcnt_hi_u32_b32 v4, -1, v192
	v_and_b32_e32 v6, 64, v4
	v_xor_b32_e32 v5, 16, v4
	v_add_u32_e32 v6, 64, v6
	v_cmp_lt_i32_e32 vcc, v5, v6
	v_lshlrev_b64 v[12:13], 10, v[132:133]
	v_readlane_b32 s44, v247, 21
	v_cndmask_b32_e32 v5, v4, v5, vcc
	v_lshlrev_b32_e32 v62, 2, v5
	v_xor_b32_e32 v5, 32, v4
	v_cmp_lt_i32_e32 vcc, v5, v6
	v_readlane_b32 s45, v247, 22
	v_readlane_b32 s46, v247, 23
	v_cndmask_b32_e32 v4, v4, v5, vcc
	v_lshlrev_b32_e32 v63, 2, v4
	v_lshlrev_b32_e32 v4, 2, v128
	v_or_b32_e32 v12, v12, v4
	v_lshl_add_u64 v[46:47], s[64:65], 0, v[12:13]
	v_lshlrev_b64 v[12:13], 12, v[138:139]
	v_readlane_b32 s47, v247, 24
	v_readlane_b32 s48, v247, 25
	v_readlane_b32 s49, v247, 26
	v_readlane_b32 s50, v247, 27
	v_readlane_b32 s51, v247, 28
	s_mov_b64 s[20:21], s[44:45]
	v_or_b32_e32 v6, 0x100, v4
	v_or_b32_e32 v8, 0x200, v4
	v_or_b32_e32 v10, 0x300, v4
	s_ashr_i32 s31, s30, 31
	v_or_b32_e32 v12, v12, v40
	v_cmp_eq_u32_e64 s[6:7], 0, v128
	v_lshl_add_u64 v[42:43], s[20:21], 0, v[40:41]
	v_lshl_add_u64 v[44:45], v[132:133], 2, s[54:55]
	s_lshl_b64 s[2:3], s[30:31], 2
	s_lshl_b64 s[4:5], s[30:31], 10
	v_lshl_add_u64 v[48:49], s[12:13], 0, v[12:13]
	s_lshl_b64 s[12:13], s[30:31], 12
	s_mov_b64 s[14:15], 0
	v_mov_b32_e32 v64, 0x358637bd
	v_lshlrev_b32_e32 v40, 2, v4
	v_lshlrev_b32_e32 v50, 2, v6
	v_mov_b32_e32 v51, v41
	v_lshlrev_b32_e32 v52, 2, v8
	v_mov_b32_e32 v53, v41
	v_lshlrev_b32_e32 v54, 2, v10
	v_mov_b32_e32 v55, v41
	s_mov_b32 s20, 0x43600000
	v_mov_b32_e32 v32, v132
	v_readlane_b32 s38, v247, 15
	v_readlane_b32 s39, v247, 16
	v_readlane_b32 s40, v247, 17
	v_readlane_b32 s41, v247, 18
	v_readlane_b32 s42, v247, 19
	v_readlane_b32 s43, v247, 20
	s_mov_b64 s[22:23], s[46:47]
	s_mov_b64 s[24:25], s[48:49]
	s_mov_b64 s[26:27], s[50:51]
	global_load_dwordx4 v[4:7], v[126:127], off
	global_load_dwordx4 v[8:11], v[126:127], off offset:1024
	global_load_dwordx4 v[12:15], v[126:127], off offset:2048
	global_load_dwordx4 v[16:19], v[126:127], off offset:3072
	v_add_u32_e32 v142, s30, v132
	v_cmp_gt_i32_e32 vcc, s19, v142
	v_lshl_add_u64 v[124:125], v[126:127], 0, s[12:13]
	s_nop 0
	v_cndmask_b32_e32 v124, v126, v124, vcc
	v_cndmask_b32_e32 v125, v127, v125, vcc
	global_load_dwordx4 v[144:147], v[124:125], off
	global_load_dwordx4 v[148:151], v[124:125], off offset:1024
	global_load_dwordx4 v[152:155], v[124:125], off offset:2048
	global_load_dwordx4 v[156:159], v[124:125], off offset:3072
	s_mov_b32 s52, 0
	s_waitcnt vmcnt(4)
	s_branch .LBB0_210
.LBB0_209:
	s_or_b64 exec, exec, s[16:17]
	s_and_b64 s[8:9], exec, s[8:9]
	s_or_b64 s[14:15], s[8:9], s[14:15]
	v_lshl_add_u64 v[44:45], v[44:45], 0, s[2:3]
	v_lshl_add_u64 v[46:47], v[46:47], 0, s[4:5]
	v_lshl_add_u64 v[48:49], v[48:49], 0, s[12:13]
	v_mov_b32_e32 v32, v65
	s_andn2_b64 exec, exec, s[14:15]
	s_cbranch_execz .LBB0_214
.LBB0_210:
	v_add_u32_e32 v65, s30, v32
	s_movk_i32 s8, 0x7fff
	v_cmp_gt_i32_e32 vcc, s19, v65
	v_cmp_lt_i32_e64 s[8:9], s8, v65
	v_ashrrev_i32_e32 v24, 11, v32
	v_mul_i32_i24_e32 v24, 0x1800, v24
	s_mov_b64 s[10:11], 0x1000
	v_ashrrev_i32_e32 v25, 31, v24
	v_lshl_add_u64 v[24:25], v[24:25], 2, s[86:87]
	v_lshl_add_u64 v[32:33], v[24:25], 0, s[10:11]
	v_lshl_add_u64 v[60:61], v[24:25], 0, v[40:41]
	v_lshl_add_u64 v[26:27], v[32:33], 0, v[40:41]
	v_lshl_add_u64 v[28:29], v[32:33], 0, v[50:51]
	v_lshl_add_u64 v[30:31], v[32:33], 0, v[52:53]
	v_lshl_add_u64 v[32:33], v[32:33], 0, v[54:55]
	global_load_dwordx4 v[76:79], v[42:43], off
	global_load_dwordx4 v[80:83], v[42:43], off offset:1024
	global_load_dwordx4 v[84:87], v[42:43], off offset:2048
	global_load_dwordx4 v[88:91], v[42:43], off offset:3072
	global_load_dwordx4 v[92:95], v[26:27], off
	global_load_dwordx4 v[96:99], v[28:29], off
	global_load_dwordx4 v[100:103], v[30:31], off
	global_load_dwordx4 v[104:107], v[32:33], off
	global_load_dwordx4 v[108:111], v[60:61], off
	global_load_dwordx4 v[112:115], v[60:61], off offset:1024
	global_load_dwordx4 v[116:119], v[60:61], off offset:2048
	global_load_dwordx4 v[120:123], v[60:61], off offset:3072
	s_waitcnt vmcnt(33)
	v_add_u32_e32 v142, s30, v65
	s_sub_u32 s24, 0, s12
	s_subb_u32 s25, 0, s13
	v_cmp_gt_i32_e64 s[62:63], s19, v142
	v_lshl_add_u64 v[124:125], v[48:49], 0, s[12:13]
	v_lshl_add_u64 v[126:127], v[48:49], 0, s[24:25]
	s_nop 0
	v_cndmask_b32_e64 v126, v126, v124, s[62:63]
	v_cndmask_b32_e64 v127, v127, v125, s[62:63]
	s_cmp_eq_u32 s52, 0
	s_cbranch_scc0 .Lp1_odd
	v_mov_b32_e32 v21, v4
	v_mov_b32_e32 v37, v5
	v_mov_b32_e32 v23, v6
	v_mov_b32_e32 v35, v7
	v_mov_b32_e32 v20, v8
	v_mov_b32_e32 v36, v9
	v_mov_b32_e32 v22, v10
	v_mov_b32_e32 v34, v11
	v_mov_b32_e32 v1, v12
	v_mov_b32_e32 v59, v13
	v_mov_b32_e32 v3, v14
	v_mov_b32_e32 v57, v15
	v_mov_b32_e32 v0, v16
	v_mov_b32_e32 v58, v17
	v_mov_b32_e32 v2, v18
	v_mov_b32_e32 v56, v19
	global_load_dwordx4 v[4:7], v[126:127], off
	global_load_dwordx4 v[8:11], v[126:127], off offset:1024
	global_load_dwordx4 v[12:15], v[126:127], off offset:2048
	global_load_dwordx4 v[16:19], v[126:127], off offset:3072
	s_branch .Lp1_j
.Lp1_odd:
	v_mov_b32_e32 v21, v144
	v_mov_b32_e32 v37, v145
	v_mov_b32_e32 v23, v146
	v_mov_b32_e32 v35, v147
	v_mov_b32_e32 v20, v148
	v_mov_b32_e32 v36, v149
	v_mov_b32_e32 v22, v150
	v_mov_b32_e32 v34, v151
	v_mov_b32_e32 v1, v152
	v_mov_b32_e32 v59, v153
	v_mov_b32_e32 v3, v154
	v_mov_b32_e32 v57, v155
	v_mov_b32_e32 v0, v156
	v_mov_b32_e32 v58, v157
	v_mov_b32_e32 v2, v158
	v_mov_b32_e32 v56, v159
	global_load_dwordx4 v[144:147], v[126:127], off
	global_load_dwordx4 v[148:151], v[126:127], off offset:1024
	global_load_dwordx4 v[152:155], v[126:127], off offset:2048
	global_load_dwordx4 v[156:159], v[126:127], off offset:3072
.Lp1_j:
	s_xor_b32 s52, s52, 1
	v_pk_mul_f32 v[24:25], v[20:21], v[20:21]
	v_pk_mul_f32 v[26:27], v[0:1], v[0:1]
	v_pk_fma_f32 v[24:25], v[36:37], v[36:37], v[24:25]
	v_pk_fma_f32 v[26:27], v[58:59], v[58:59], v[26:27]
	v_pk_fma_f32 v[24:25], v[22:23], v[22:23], v[24:25]
	v_pk_fma_f32 v[26:27], v[2:3], v[2:3], v[26:27]
	v_pk_fma_f32 v[24:25], v[34:35], v[34:35], v[24:25]
	v_pk_fma_f32 v[26:27], v[56:57], v[56:57], v[26:27]
	v_add_f32_e32 v24, v24, v25
	v_add_f32_e32 v24, v27, v24
	v_add_f32_e32 v24, v26, v24
	s_mov_b32 s10, 0x800000
	v_add_f32_dpp v24, v24, v24 row_ror:8 row_mask:0xf bank_mask:0xf bound_ctrl:1
	s_nop 1
	v_add_f32_dpp v24, v24, v24 row_ror:4 row_mask:0xf bank_mask:0xf bound_ctrl:1
	s_nop 1
	v_add_f32_dpp v24, v24, v24 row_ror:2 row_mask:0xf bank_mask:0xf bound_ctrl:1
	s_nop 1
	v_add_f32_dpp v24, v24, v24 row_ror:1 row_mask:0xf bank_mask:0xf bound_ctrl:1
	ds_bpermute_b32 v25, v62, v24
	s_waitcnt lgkmcnt(0)
	v_add_f32_e32 v24, v24, v25
	ds_bpermute_b32 v25, v63, v24
	s_waitcnt lgkmcnt(0)
	v_add_f32_e32 v24, v24, v25
	v_fmamk_f32 v24, v24, 0x3a800000, v64
	v_cmp_gt_f32_e32 vcc, s10, v24
	v_mul_f32_e32 v25, 0x4b800000, v24
	v_cndmask_b32_e32 v24, v24, v25, vcc
	v_rsq_f32_e32 v24, v24
	s_nop 0
	v_mul_f32_e32 v25, 0x45800000, v24
	v_cndmask_b32_e32 v66, v24, v25, vcc
	s_waitcnt vmcnt(4)
	v_mul_f32_e32 v142, v21, v66
	v_add_f32_e32 v143, 1.0, v92
	v_mul_f32_e32 v142, v76, v142
	v_fma_f32 v24, v143, v142, v108
	v_mul_f32_e32 v142, v37, v66
	v_add_f32_e32 v143, 1.0, v93
	v_mul_f32_e32 v142, v77, v142
	v_fma_f32 v25, v143, v142, v109
	v_mul_f32_e32 v142, v23, v66
	v_add_f32_e32 v143, 1.0, v94
	v_mul_f32_e32 v142, v78, v142
	v_fma_f32 v26, v143, v142, v110
	v_mul_f32_e32 v142, v35, v66
	v_add_f32_e32 v143, 1.0, v95
	v_mul_f32_e32 v142, v79, v142
	v_fma_f32 v27, v143, v142, v111
	v_mul_f32_e32 v142, v20, v66
	v_add_f32_e32 v143, 1.0, v96
	v_mul_f32_e32 v142, v80, v142
	v_fma_f32 v28, v143, v142, v112
	v_mul_f32_e32 v142, v36, v66
	v_add_f32_e32 v143, 1.0, v97
	v_mul_f32_e32 v142, v81, v142
	v_fma_f32 v67, v143, v142, v113
	v_mul_f32_e32 v142, v22, v66
	v_add_f32_e32 v143, 1.0, v98
	v_mul_f32_e32 v142, v82, v142
	v_fma_f32 v29, v143, v142, v114
	v_mul_f32_e32 v142, v34, v66
	v_add_f32_e32 v143, 1.0, v99
	v_mul_f32_e32 v142, v83, v142
	v_fma_f32 v31, v143, v142, v115
	v_mul_f32_e32 v142, v1, v66
	v_add_f32_e32 v143, 1.0, v100
	v_mul_f32_e32 v142, v84, v142
	v_fma_f32 v1, v143, v142, v116
	v_mul_f32_e32 v142, v59, v66
	v_add_f32_e32 v143, 1.0, v101
	v_mul_f32_e32 v142, v85, v142
	v_fma_f32 v59, v143, v142, v117
	v_mul_f32_e32 v142, v3, v66
	v_add_f32_e32 v143, 1.0, v102
	v_mul_f32_e32 v142, v86, v142
	v_fma_f32 v3, v143, v142, v118
	v_mul_f32_e32 v142, v57, v66
	v_add_f32_e32 v143, 1.0, v103
	v_mul_f32_e32 v142, v87, v142
	v_fma_f32 v23, v143, v142, v119
	v_mul_f32_e32 v142, v0, v66
	v_add_f32_e32 v143, 1.0, v104
	v_mul_f32_e32 v142, v88, v142
	v_fma_f32 v20, v143, v142, v120
	v_mul_f32_e32 v142, v58, v66
	v_add_f32_e32 v143, 1.0, v105
	v_mul_f32_e32 v142, v89, v142
	v_fma_f32 v21, v143, v142, v121
	v_mul_f32_e32 v142, v2, v66
	v_add_f32_e32 v143, 1.0, v106
	v_mul_f32_e32 v142, v90, v142
	v_fma_f32 v2, v143, v142, v122
	v_mul_f32_e32 v142, v56, v66
	v_add_f32_e32 v143, 1.0, v107
	v_mul_f32_e32 v142, v91, v142
	v_fma_f32 v35, v143, v142, v123
	v_max_f32_e64 v30, |v26|, |v27|
	v_max3_f32 v30, |v24|, |v25|, v30
	v_max3_f32 v30, |v28|, |v67|, v30
	v_max3_f32 v30, |v29|, |v31|, v30
	v_max3_f32 v30, |v1|, |v59|, v30
	v_max3_f32 v30, |v3|, |v23|, v30
	v_max3_f32 v30, |v20|, |v21|, v30
	v_max3_f32 v0, |v2|, |v35|, v30
	s_nop 1
	v_mov_b32_dpp v22, v0 row_ror:8 row_mask:0xf bank_mask:0xf bound_ctrl:1
	v_max_f32_e32 v22, v22, v22
	v_max_f32_e32 v0, v0, v22
	s_nop 1
	v_mov_b32_dpp v22, v0 row_ror:4 row_mask:0xf bank_mask:0xf bound_ctrl:1
	v_max_f32_e32 v22, v22, v22
	v_max_f32_e32 v0, v0, v22
	s_nop 1
	v_mov_b32_dpp v22, v0 row_ror:2 row_mask:0xf bank_mask:0xf bound_ctrl:1
	v_max_f32_e32 v22, v22, v22
	v_max_f32_e32 v0, v0, v22
	s_nop 1
	v_mov_b32_dpp v22, v0 row_ror:1 row_mask:0xf bank_mask:0xf bound_ctrl:1
	v_max_f32_e32 v22, v22, v22
	v_max_f32_e32 v0, v0, v22
	ds_bpermute_b32 v22, v62, v0
	s_waitcnt lgkmcnt(0)
	v_max_f32_e32 v22, v22, v22
	v_max_f32_e32 v0, v0, v22
	ds_bpermute_b32 v22, v63, v0
	s_waitcnt lgkmcnt(0)
	v_max_f32_e32 v22, v22, v22
	v_max_f32_e32 v0, v0, v22
	v_div_scale_f32 v22, s[16:17], v0, v0, s20
	v_rcp_f32_e32 v30, v22
	v_cmp_lt_f32_e64 s[10:11], 0, v0
	v_fma_f32 v32, -v22, v30, 1.0
	v_fmac_f32_e32 v30, v32, v30
	v_div_scale_f32 v32, vcc, s20, v0, s20
	v_mul_f32_e32 v33, v32, v30
	v_fma_f32 v34, -v22, v33, v32
	v_fmac_f32_e32 v33, v34, v30
	v_fma_f32 v22, -v22, v33, v32
	v_div_fmas_f32 v22, v22, v30, v33
	v_div_fixup_f32 v22, v22, v0, s20
	v_cndmask_b32_e64 v22, 1.0, v22, s[10:11]
	v_mul_f32_e32 v24, v24, v22
	v_mul_f32_e32 v25, v25, v22
	v_mov_b32_e32 v30, 0
	v_cvt_pk_fp8_f32 v30, v24, v25
	v_mul_f32_e32 v24, v26, v22
	v_mul_f32_e32 v25, v27, v22
	v_mov_b32_e32 v26, 0
	v_cvt_pk_fp8_f32 v30, v24, v25 op_sel:[0,0,1]
	v_mul_f32_e32 v24, v28, v22
	v_mul_f32_e32 v25, v67, v22
	v_cvt_pk_fp8_f32 v26, v24, v25
	v_mul_f32_e32 v24, v29, v22
	v_mul_f32_e32 v25, v31, v22
	v_mul_f32_e32 v1, v1, v22
	v_cvt_pk_fp8_f32 v26, v24, v25 op_sel:[0,0,1]
	v_mul_f32_e32 v24, v59, v22
	v_mov_b32_e32 v25, 0
	v_cvt_pk_fp8_f32 v25, v1, v24
	v_mul_f32_e32 v1, v3, v22
	v_mul_f32_e32 v3, v23, v22
	global_store_dword v[46:47], v30, off
	v_cvt_pk_fp8_f32 v25, v1, v3 op_sel:[0,0,1]
	v_mul_f32_e32 v1, v20, v22
	v_mul_f32_e32 v3, v21, v22
	v_mov_b32_e32 v20, 0
	v_cvt_pk_fp8_f32 v20, v1, v3
	v_mul_f32_e32 v1, v2, v22
	v_mul_f32_e32 v2, v35, v22
	global_store_dword v[46:47], v26, off offset:256
	v_cvt_pk_fp8_f32 v20, v1, v2 op_sel:[0,0,1]
	global_store_dword v[46:47], v25, off offset:512
	global_store_dword v[46:47], v20, off offset:768
	s_and_saveexec_b64 s[16:17], s[6:7]
	s_cbranch_execz .LBB0_209
	v_mul_f32_e32 v0, 0x3b924925, v0
	v_cndmask_b32_e64 v0, 1.0, v0, s[10:11]
	global_store_dword v[44:45], v0, off
	s_branch .LBB0_209
.LBB0_214:
	s_waitcnt vmcnt(0)
	s_or_b64 exec, exec, s[0:1]
	v_readlane_b32 s0, v247, 0
	s_cmpk_gt_i32 s0, 0x77f
	v_add_u32_e32 v141, 4, v129
	v_add_u32_e32 v178, 8, v129
	v_add_u32_e32 v179, 12, v129
	v_or_b32_e32 v180, 16, v129
	v_add_u32_e32 v181, 20, v129
	v_add_u32_e32 v182, 24, v129
	v_add_u32_e32 v183, 28, v129
	v_or_b32_e32 v184, 32, v129
	v_add_u32_e32 v185, 36, v129
	v_add_u32_e32 v186, 40, v129
	v_add_u32_e32 v187, 44, v129
	v_or_b32_e32 v188, 48, v129
	v_add_u32_e32 v189, 52, v129
	v_add_u32_e32 v190, 56, v129
	v_add_u32_e32 v191, 60, v129
	v_lshrrev_b32_e32 v136, 4, v130
	v_readlane_b32 s1, v247, 1
	s_cbranch_scc1 .LBB0_225
	v_lshlrev_b32_e32 v0, 2, v128
	s_movk_i32 s0, 0x104
	v_and_b32_e32 v2, 60, v140
	v_lshlrev_b32_e32 v4, 2, v136
	v_mad_u32_u24 v14, v129, s0, v0
	v_mad_u32_u24 v15, v2, s0, v4
	v_readlane_b32 s0, v247, 13
	v_mov_b32_e32 v1, 0
	v_readlane_b32 s1, v247, 14
	v_readlane_b32 s2, v247, 15
	v_readlane_b32 s3, v247, 16
	v_readlane_b32 s4, v247, 17
	v_readlane_b32 s5, v247, 18
	v_readlane_b32 s6, v247, 19
	v_readlane_b32 s7, v247, 20
	v_readlane_b32 s8, v247, 21
	v_readlane_b32 s9, v247, 22
	v_readlane_b32 s10, v247, 23
	v_readlane_b32 s11, v247, 24
	v_readlane_b32 s12, v247, 25
	v_readlane_b32 s13, v247, 26
	v_readlane_b32 s14, v247, 27
	v_readlane_b32 s15, v247, 28
	v_lshl_add_u64 v[4:5], s[10:11], 0, v[0:1]
	v_readlane_b32 s0, v247, 61
	v_readlane_b32 s2, v247, 63
	v_readlane_b32 s3, v248, 0
	v_mov_b32_e32 v3, v1
	v_readlane_b32 s1, v247, 62
	v_readlane_b32 s8, v248, 5
	v_readlane_b32 s9, v248, 6
	v_readlane_b32 s10, v248, 7
	v_readlane_b32 s11, v248, 8
	v_readlane_b32 s2, v247, 0
	v_add_u32_e32 v16, 16, v136
	v_add_u32_e32 v17, 32, v136
	v_add_u32_e32 v18, 48, v136
	v_lshl_add_u64 v[6:7], s[10:11], 0, v[2:3]
	v_mov_b32_e32 v137, v1
	s_mov_b32 s1, 0
	s_mov_b32 s8, 0x43600000
	s_mov_b32 s9, s2
	v_readlane_b32 s4, v248, 1
	v_readlane_b32 s5, v248, 2
	v_readlane_b32 s6, v248, 3
	v_readlane_b32 s7, v248, 4
	v_readlane_b32 s12, v248, 9
	v_readlane_b32 s13, v248, 10
	v_readlane_b32 s14, v248, 11
	v_readlane_b32 s15, v248, 12
	v_readlane_b32 s3, v247, 1
	s_branch .LBB0_217
